# stack + p3 epilogue hoist + accumulator reset with v_mov_b64 (P1,P4,P5,P6)
# speedup vs baseline: 1.0111x; 1.0111x over previous
.LBB0_123:
	s_add_u32 s12, s10, 0x100
	v_mov_b32_e32 v0, 0
	s_addc_u32 s13, s11, 0
	s_mov_b32 s14, 0
	s_mov_b64 s[6:7], 0
	v_mov_b32_e32 v1, v0
	v_mov_b64_e32 v[2:3], v[0:1]
	v_mov_b64_e32 v[4:5], v[0:1]
	v_mov_b64_e32 v[6:7], v[0:1]
	v_mov_b64_e32 v[8:9], v[0:1]
	v_mov_b64_e32 v[10:11], v[0:1]
	v_mov_b64_e32 v[12:13], v[0:1]
	v_mov_b64_e32 v[14:15], v[0:1]
	v_mov_b64_e32 v[16:17], v[0:1]
	v_mov_b64_e32 v[18:19], v[0:1]
	v_mov_b64_e32 v[20:21], v[0:1]
	v_mov_b64_e32 v[22:23], v[0:1]
	v_mov_b64_e32 v[24:25], v[0:1]
	v_mov_b64_e32 v[26:27], v[0:1]
	v_mov_b64_e32 v[28:29], v[0:1]
	v_mov_b64_e32 v[30:31], v[0:1]
	v_mov_b64_e32 v[32:33], v[0:1]
	v_mov_b64_e32 v[34:35], v[0:1]
	v_mov_b64_e32 v[36:37], v[0:1]
	v_mov_b64_e32 v[38:39], v[0:1]
	v_mov_b64_e32 v[40:41], v[0:1]
	v_mov_b64_e32 v[42:43], v[0:1]
	v_mov_b64_e32 v[44:45], v[0:1]
	v_mov_b64_e32 v[46:47], v[0:1]
	v_mov_b64_e32 v[48:49], v[0:1]
	v_mov_b64_e32 v[50:51], v[0:1]
	v_mov_b64_e32 v[52:53], v[0:1]
	v_mov_b64_e32 v[54:55], v[0:1]
	v_mov_b64_e32 v[56:57], v[0:1]
	v_mov_b64_e32 v[58:59], v[0:1]
	v_mov_b64_e32 v[60:61], v[0:1]
	v_mov_b64_e32 v[62:63], v[0:1]
	v_mov_b64_e32 v[64:65], v[0:1]
	v_mov_b64_e32 v[66:67], v[0:1]
	v_mov_b64_e32 v[68:69], v[0:1]
	v_mov_b64_e32 v[70:71], v[0:1]
	v_mov_b64_e32 v[72:73], v[0:1]
	v_mov_b64_e32 v[74:75], v[0:1]
	v_mov_b64_e32 v[76:77], v[0:1]
	v_mov_b64_e32 v[78:79], v[0:1]
	v_mov_b64_e32 v[80:81], v[0:1]
	v_mov_b64_e32 v[82:83], v[0:1]
	v_mov_b64_e32 v[84:85], v[0:1]
	v_mov_b64_e32 v[86:87], v[0:1]
	v_mov_b64_e32 v[88:89], v[0:1]
	v_mov_b64_e32 v[90:91], v[0:1]
	v_mov_b64_e32 v[92:93], v[0:1]
	v_mov_b64_e32 v[94:95], v[0:1]
	v_mov_b64_e32 v[96:97], v[0:1]
	v_mov_b64_e32 v[98:99], v[0:1]
	v_mov_b64_e32 v[100:101], v[0:1]
	v_mov_b64_e32 v[102:103], v[0:1]
	v_mov_b64_e32 v[104:105], v[0:1]
	v_mov_b64_e32 v[106:107], v[0:1]
	v_mov_b64_e32 v[108:109], v[0:1]
	v_mov_b64_e32 v[110:111], v[0:1]
	v_mov_b64_e32 v[112:113], v[0:1]
	v_mov_b64_e32 v[114:115], v[0:1]
	v_mov_b64_e32 v[116:117], v[0:1]
	v_mov_b64_e32 v[118:119], v[0:1]
	v_mov_b64_e32 v[120:121], v[0:1]
	v_mov_b64_e32 v[122:123], v[0:1]
	v_mov_b64_e32 v[124:125], v[0:1]
	v_mov_b64_e32 v[126:127], v[0:1]
	v_lshl_add_u64 v[156:157], s[8:9], 0, v[146:147]
	v_lshl_add_u64 v[158:159], s[8:9], 0, v[148:149]

.LBB0_503:
	s_ashr_i32 s31, s30, 31
	s_lshl_b64 s[34:35], s[30:31], 19
	s_add_u32 s34, s60, s34
	s_addc_u32 s35, s61, s35
	s_ashr_i32 s29, s28, 31
	s_lshl_b64 s[36:37], s[28:29], 19
	v_readlane_b32 s46, v255, 26
	v_readlane_b32 s47, v255, 27
	s_add_u32 s36, s46, s36
	s_addc_u32 s37, s47, s37
	s_and_b64 s[46:47], s[6:7], exec
	s_cselect_b32 s19, s37, s45
	s_cselect_b32 s29, s36, s44
	s_add_u32 s31, s44, 0x100
	v_mov_b32_e32 v0, 0
	v_lshl_add_u64 v[128:129], s[42:43], 0, v[184:185]
	v_lshl_add_u64 v[130:131], s[42:43], 0, v[186:187]
	s_addc_u32 s39, s45, 0
	s_mov_b32 s63, 0
	s_mov_b64 s[44:45], 0
	s_waitcnt lgkmcnt(0)
	v_mov_b32_e32 v1, v0
	v_mov_b64_e32 v[2:3], v[0:1]
	v_mov_b64_e32 v[4:5], v[0:1]
	v_mov_b64_e32 v[6:7], v[0:1]
	v_mov_b64_e32 v[8:9], v[0:1]
	v_mov_b64_e32 v[10:11], v[0:1]
	v_mov_b64_e32 v[12:13], v[0:1]
	v_mov_b64_e32 v[14:15], v[0:1]
	v_mov_b64_e32 v[16:17], v[0:1]
	v_mov_b64_e32 v[18:19], v[0:1]
	v_mov_b64_e32 v[20:21], v[0:1]
	v_mov_b64_e32 v[22:23], v[0:1]
	v_mov_b64_e32 v[24:25], v[0:1]
	v_mov_b64_e32 v[26:27], v[0:1]
	v_mov_b64_e32 v[28:29], v[0:1]
	v_mov_b64_e32 v[30:31], v[0:1]
	v_mov_b64_e32 v[32:33], v[0:1]
	v_mov_b64_e32 v[34:35], v[0:1]
	v_mov_b64_e32 v[36:37], v[0:1]
	v_mov_b64_e32 v[38:39], v[0:1]
	v_mov_b64_e32 v[40:41], v[0:1]
	v_mov_b64_e32 v[42:43], v[0:1]
	v_mov_b64_e32 v[44:45], v[0:1]
	v_mov_b64_e32 v[46:47], v[0:1]
	v_mov_b64_e32 v[48:49], v[0:1]
	v_mov_b64_e32 v[50:51], v[0:1]
	v_mov_b64_e32 v[52:53], v[0:1]
	v_mov_b64_e32 v[54:55], v[0:1]
	v_mov_b64_e32 v[56:57], v[0:1]
	v_mov_b64_e32 v[58:59], v[0:1]
	v_mov_b64_e32 v[60:61], v[0:1]
	v_mov_b64_e32 v[62:63], v[0:1]
	v_mov_b64_e32 v[64:65], v[0:1]
	v_mov_b64_e32 v[66:67], v[0:1]
	v_mov_b64_e32 v[68:69], v[0:1]
	v_mov_b64_e32 v[70:71], v[0:1]
	v_mov_b64_e32 v[72:73], v[0:1]
	v_mov_b64_e32 v[74:75], v[0:1]
	v_mov_b64_e32 v[76:77], v[0:1]
	v_mov_b64_e32 v[78:79], v[0:1]
	v_mov_b64_e32 v[80:81], v[0:1]
	v_mov_b64_e32 v[82:83], v[0:1]
	v_mov_b64_e32 v[84:85], v[0:1]
	v_mov_b64_e32 v[86:87], v[0:1]
	v_mov_b64_e32 v[88:89], v[0:1]
	v_mov_b64_e32 v[90:91], v[0:1]
	v_mov_b64_e32 v[92:93], v[0:1]
	v_mov_b64_e32 v[94:95], v[0:1]
	v_mov_b64_e32 v[96:97], v[0:1]
	v_mov_b64_e32 v[98:99], v[0:1]
	v_mov_b64_e32 v[100:101], v[0:1]
	v_mov_b64_e32 v[102:103], v[0:1]
	v_mov_b64_e32 v[104:105], v[0:1]
	v_mov_b64_e32 v[106:107], v[0:1]
	v_mov_b64_e32 v[108:109], v[0:1]
	v_mov_b64_e32 v[110:111], v[0:1]
	v_mov_b64_e32 v[112:113], v[0:1]
	v_mov_b64_e32 v[114:115], v[0:1]
	v_mov_b64_e32 v[116:117], v[0:1]
	v_mov_b64_e32 v[118:119], v[0:1]
	v_mov_b64_e32 v[120:121], v[0:1]
	v_mov_b64_e32 v[122:123], v[0:1]
	v_mov_b64_e32 v[124:125], v[0:1]
	v_mov_b64_e32 v[126:127], v[0:1]

.LBB0_598:
	s_ashr_i32 s27, s26, 31
	s_lshl_b64 s[28:29], s[26:27], 19
	s_add_u32 s28, s12, s28
	s_addc_u32 s29, s13, s29
	s_ashr_i32 s25, s24, 31
	s_lshl_b64 s[30:31], s[24:25], 19
	v_readlane_b32 s40, v255, 28
	v_readlane_b32 s41, v255, 29
	s_add_u32 s30, s40, s30
	s_addc_u32 s31, s41, s31
	s_and_b64 s[40:41], s[4:5], exec
	s_cselect_b32 s25, s31, s39
	s_cselect_b32 s27, s30, s38
	s_add_u32 s57, s38, 0x100
	v_mov_b32_e32 v0, 0
	v_lshl_add_u64 v[144:145], s[36:37], 0, v[136:137]
	v_lshl_add_u64 v[146:147], s[36:37], 0, v[138:139]
	s_addc_u32 s58, s39, 0
	s_mov_b32 s59, 0
	s_mov_b64 s[38:39], 0
	v_mov_b32_e32 v1, v0
	v_mov_b64_e32 v[2:3], v[0:1]
	v_mov_b64_e32 v[4:5], v[0:1]
	v_mov_b64_e32 v[6:7], v[0:1]
	v_mov_b64_e32 v[8:9], v[0:1]
	v_mov_b64_e32 v[10:11], v[0:1]
	v_mov_b64_e32 v[12:13], v[0:1]
	v_mov_b64_e32 v[14:15], v[0:1]
	v_mov_b64_e32 v[16:17], v[0:1]
	v_mov_b64_e32 v[18:19], v[0:1]
	v_mov_b64_e32 v[20:21], v[0:1]
	v_mov_b64_e32 v[22:23], v[0:1]
	v_mov_b64_e32 v[24:25], v[0:1]
	v_mov_b64_e32 v[26:27], v[0:1]
	v_mov_b64_e32 v[28:29], v[0:1]
	v_mov_b64_e32 v[30:31], v[0:1]
	v_mov_b64_e32 v[32:33], v[0:1]
	v_mov_b64_e32 v[34:35], v[0:1]
	v_mov_b64_e32 v[36:37], v[0:1]
	v_mov_b64_e32 v[38:39], v[0:1]
	v_mov_b64_e32 v[40:41], v[0:1]
	v_mov_b64_e32 v[42:43], v[0:1]
	v_mov_b64_e32 v[44:45], v[0:1]
	v_mov_b64_e32 v[46:47], v[0:1]
	v_mov_b64_e32 v[48:49], v[0:1]
	v_mov_b64_e32 v[50:51], v[0:1]
	v_mov_b64_e32 v[52:53], v[0:1]
	v_mov_b64_e32 v[54:55], v[0:1]
	v_mov_b64_e32 v[56:57], v[0:1]
	v_mov_b64_e32 v[58:59], v[0:1]
	v_mov_b64_e32 v[60:61], v[0:1]
	v_mov_b64_e32 v[62:63], v[0:1]
	v_mov_b64_e32 v[64:65], v[0:1]
	v_mov_b64_e32 v[66:67], v[0:1]
	v_mov_b64_e32 v[68:69], v[0:1]
	v_mov_b64_e32 v[70:71], v[0:1]
	v_mov_b64_e32 v[72:73], v[0:1]
	v_mov_b64_e32 v[74:75], v[0:1]
	v_mov_b64_e32 v[76:77], v[0:1]
	v_mov_b64_e32 v[78:79], v[0:1]
	v_mov_b64_e32 v[80:81], v[0:1]
	v_mov_b64_e32 v[82:83], v[0:1]
	v_mov_b64_e32 v[84:85], v[0:1]
	v_mov_b64_e32 v[86:87], v[0:1]
	v_mov_b64_e32 v[88:89], v[0:1]
	v_mov_b64_e32 v[90:91], v[0:1]
	v_mov_b64_e32 v[92:93], v[0:1]
	v_mov_b64_e32 v[94:95], v[0:1]
	v_mov_b64_e32 v[96:97], v[0:1]
	v_mov_b64_e32 v[98:99], v[0:1]
	v_mov_b64_e32 v[100:101], v[0:1]
	v_mov_b64_e32 v[102:103], v[0:1]
	v_mov_b64_e32 v[104:105], v[0:1]
	v_mov_b64_e32 v[106:107], v[0:1]
	v_mov_b64_e32 v[108:109], v[0:1]
	v_mov_b64_e32 v[110:111], v[0:1]
	v_mov_b64_e32 v[112:113], v[0:1]
	v_mov_b64_e32 v[114:115], v[0:1]
	v_mov_b64_e32 v[116:117], v[0:1]
	v_mov_b64_e32 v[118:119], v[0:1]
	v_mov_b64_e32 v[120:121], v[0:1]
	v_mov_b64_e32 v[122:123], v[0:1]
	v_mov_b64_e32 v[124:125], v[0:1]
	v_mov_b64_e32 v[126:127], v[0:1]

.LBB0_677:
	s_ashr_i32 s11, s10, 31
	s_lshl_b64 s[14:15], s[10:11], 15
	s_add_u32 s14, s52, s14
	s_addc_u32 s15, s53, s15
	s_ashr_i32 s9, s8, 31
	s_lshl_b64 s[16:17], s[8:9], 15
	s_add_u32 s16, s50, s16
	s_addc_u32 s17, s51, s17
	s_and_b64 s[24:25], s[4:5], exec
	s_cselect_b32 s9, s17, s23
	s_cselect_b32 s11, s16, s22
	s_add_u32 s42, s22, 0x40000
	v_mov_b32_e32 v0, 0
	v_lshl_add_u64 v[140:141], s[20:21], 0, v[132:133]
	v_lshl_add_u64 v[142:143], s[20:21], 0, v[134:135]
	s_addc_u32 s43, s23, 0
	s_mov_b32 s44, 0
	s_mov_b64 s[22:23], 0x204000
	v_mov_b32_e32 v1, v0
	v_mov_b64_e32 v[2:3], v[0:1]
	v_mov_b64_e32 v[4:5], v[0:1]
	v_mov_b64_e32 v[6:7], v[0:1]
	v_mov_b64_e32 v[8:9], v[0:1]
	v_mov_b64_e32 v[10:11], v[0:1]
	v_mov_b64_e32 v[12:13], v[0:1]
	v_mov_b64_e32 v[14:15], v[0:1]
	v_mov_b64_e32 v[16:17], v[0:1]
	v_mov_b64_e32 v[18:19], v[0:1]
	v_mov_b64_e32 v[20:21], v[0:1]
	v_mov_b64_e32 v[22:23], v[0:1]
	v_mov_b64_e32 v[24:25], v[0:1]
	v_mov_b64_e32 v[26:27], v[0:1]
	v_mov_b64_e32 v[28:29], v[0:1]
	v_mov_b64_e32 v[30:31], v[0:1]
	v_mov_b64_e32 v[32:33], v[0:1]
	v_mov_b64_e32 v[34:35], v[0:1]
	v_mov_b64_e32 v[36:37], v[0:1]
	v_mov_b64_e32 v[38:39], v[0:1]
	v_mov_b64_e32 v[40:41], v[0:1]
	v_mov_b64_e32 v[42:43], v[0:1]
	v_mov_b64_e32 v[44:45], v[0:1]
	v_mov_b64_e32 v[46:47], v[0:1]
	v_mov_b64_e32 v[48:49], v[0:1]
	v_mov_b64_e32 v[50:51], v[0:1]
	v_mov_b64_e32 v[52:53], v[0:1]
	v_mov_b64_e32 v[54:55], v[0:1]
	v_mov_b64_e32 v[56:57], v[0:1]
	v_mov_b64_e32 v[58:59], v[0:1]
	v_mov_b64_e32 v[60:61], v[0:1]
	v_mov_b64_e32 v[62:63], v[0:1]
	v_mov_b64_e32 v[64:65], v[0:1]
	v_mov_b64_e32 v[66:67], v[0:1]
	v_mov_b64_e32 v[68:69], v[0:1]
	v_mov_b64_e32 v[70:71], v[0:1]
	v_mov_b64_e32 v[72:73], v[0:1]
	v_mov_b64_e32 v[74:75], v[0:1]
	v_mov_b64_e32 v[76:77], v[0:1]
	v_mov_b64_e32 v[78:79], v[0:1]
	v_mov_b64_e32 v[80:81], v[0:1]
	v_mov_b64_e32 v[82:83], v[0:1]
	v_mov_b64_e32 v[84:85], v[0:1]
	v_mov_b64_e32 v[86:87], v[0:1]
	v_mov_b64_e32 v[88:89], v[0:1]
	v_mov_b64_e32 v[90:91], v[0:1]
	v_mov_b64_e32 v[92:93], v[0:1]
	v_mov_b64_e32 v[94:95], v[0:1]
	v_mov_b64_e32 v[96:97], v[0:1]
	v_mov_b64_e32 v[98:99], v[0:1]
	v_mov_b64_e32 v[100:101], v[0:1]
	v_mov_b64_e32 v[102:103], v[0:1]
	v_mov_b64_e32 v[104:105], v[0:1]
	v_mov_b64_e32 v[106:107], v[0:1]
	v_mov_b64_e32 v[108:109], v[0:1]
	v_mov_b64_e32 v[110:111], v[0:1]
	v_mov_b64_e32 v[112:113], v[0:1]
	v_mov_b64_e32 v[114:115], v[0:1]
	v_mov_b64_e32 v[116:117], v[0:1]
	v_mov_b64_e32 v[118:119], v[0:1]
	v_mov_b64_e32 v[120:121], v[0:1]
	v_mov_b64_e32 v[122:123], v[0:1]
	v_mov_b64_e32 v[124:125], v[0:1]
	v_mov_b64_e32 v[126:127], v[0:1]
